# attention inner loops: removed no-op lgkmcnt waits in QK sections, dropped m0 save/restore around LDS-DMA, removed sum+0, one V-fragment wait per tile in no-max loop
# speedup vs baseline: 1.0091x; 1.0038x over previous
.LBB0_477:
	s_lshl_b32 s22, s22, 1
	v_add_u32_e32 v212, s22, v245
	ds_read_b64_tr_b16 v[208:209], v212 offset:24576
	ds_read_b64_tr_b16 v[210:211], v212 offset:25088
	v_mfma_f32_32x32x16_bf16 v[128:143], v[204:207], v[172:175], v[64:79]
	v_add_f32_e32 v112, v96, v97
	v_add_f32_e32 v112, v98, v112
	v_add_f32_e32 v112, v99, v112
	v_add_f32_e32 v112, v100, v112
	v_add_f32_e32 v112, v101, v112
	v_cvt_pk_bf16_f32 v156, v96, v97
	v_cvt_pk_bf16_f32 v157, v98, v99
	ds_read_b64_tr_b16 v[204:205], v212 offset:28672
	ds_read_b64_tr_b16 v[206:207], v212 offset:29184
	v_add_f32_e32 v96, v102, v112
	v_mfma_f32_32x32x16_bf16 v[112:127], v[196:199], v[172:175], v[64:79]
	v_add_f32_e32 v96, v103, v96
	v_add_f32_e32 v96, v104, v96
	v_add_f32_e32 v96, v105, v96
	v_cvt_pk_bf16_f32 v158, v100, v101
	v_cvt_pk_bf16_f32 v159, v102, v103
	ds_read_b64_tr_b16 v[100:101], v212 offset:25600
	ds_read_b64_tr_b16 v[102:103], v212 offset:26112
	v_mfma_f32_32x32x16_bf16 v[128:143], v[200:203], v[168:171], v[128:143]
	v_add_f32_e32 v96, v106, v96
	v_add_f32_e32 v96, v107, v96
	v_add_f32_e32 v96, v108, v96
	v_add_f32_e32 v144, v109, v96
	v_cvt_pk_bf16_f32 v152, v104, v105
	v_cvt_pk_bf16_f32 v153, v106, v107
	ds_read_b64_tr_b16 v[96:97], v212 offset:29696
	ds_read_b64_tr_b16 v[98:99], v212 offset:30208
	v_mfma_f32_32x32x16_bf16 v[112:127], v[192:195], v[168:171], v[112:127]
	v_add_f32_e32 v104, v110, v144
	v_add_f32_e32 v104, v111, v104
	v_add_f32_e32 v104, v80, v104
	v_add_f32_e32 v104, v81, v104
	v_cvt_pk_bf16_f32 v154, v108, v109
	v_cvt_pk_bf16_f32 v155, v110, v111
	ds_read_b64_tr_b16 v[108:109], v212 offset:26624
	ds_read_b64_tr_b16 v[110:111], v212 offset:27136
	v_mfma_f32_32x32x16_bf16 v[128:143], v[188:191], v[164:167], v[128:143]
	v_add_f32_e32 v104, v82, v104
	v_add_f32_e32 v104, v83, v104
	v_add_f32_e32 v104, v84, v104
	v_add_f32_e32 v144, v85, v104
	v_cvt_pk_bf16_f32 v148, v80, v81
	v_cvt_pk_bf16_f32 v149, v82, v83
	ds_read_b64_tr_b16 v[104:105], v212 offset:30720
	ds_read_b64_tr_b16 v[106:107], v212 offset:31232
	v_mfma_f32_32x32x16_bf16 v[112:127], v[184:187], v[164:167], v[112:127]
	v_add_f32_e32 v80, v86, v144
	v_add_f32_e32 v80, v87, v80
	v_add_f32_e32 v80, v88, v80
	v_add_f32_e32 v80, v89, v80
	v_cvt_pk_bf16_f32 v150, v84, v85
	v_cvt_pk_bf16_f32 v151, v86, v87
	ds_read_b64_tr_b16 v[84:85], v212 offset:27648
	ds_read_b64_tr_b16 v[86:87], v212 offset:28160
	v_mfma_f32_32x32x16_bf16 v[128:143], v[180:183], v[160:163], v[128:143]
	v_add_f32_e32 v80, v90, v80
	v_add_f32_e32 v80, v91, v80
	v_add_f32_e32 v80, v92, v80
	v_add_f32_e32 v80, v93, v80
	v_cvt_pk_bf16_f32 v144, v88, v89
	v_cvt_pk_bf16_f32 v145, v90, v91
	ds_read_b64_tr_b16 v[88:89], v212 offset:31744
	ds_read_b64_tr_b16 v[90:91], v212 offset:32256
	v_mfma_f32_32x32x16_bf16 v[112:127], v[176:179], v[160:163], v[112:127]
	v_add_f32_e32 v80, v94, v80
	v_add_f32_e32 v80, v95, v80
	v_cvt_pk_bf16_f32 v146, v92, v93
	v_cvt_pk_bf16_f32 v147, v94, v95
	v_max_f32_e32 v81, v129, v129
	v_max_f32_e32 v82, v128, v128
	v_max_f32_e32 v81, v82, v81
	s_nop 3
	v_max3_f32 v82, v130, v131, v113
	v_max3_f32 v81, v81, v112, v114
	v_max3_f32 v81, v81, v115, v132
	v_max3_f32 v82, v82, v134, v135
	s_add_u32 s37, s16, s24
	v_max3_f32 v81, v81, v133, v116
	v_max3_f32 v82, v82, v118, v119
	s_addc_u32 s39, s17, s19
	v_max3_f32 v81, v81, v117, v136
	v_max3_f32 v82, v82, v138, v139
	s_add_u32 s22, s37, 0x9b80800
	v_max3_f32 v81, v81, v137, v120
	v_max3_f32 v82, v82, v122, v123
	s_addc_u32 s23, s39, 0
	s_add_i32 s34, s33, s28
	s_mov_b32 m0, s34
	s_nop 0
	global_load_lds_dwordx4 v241, s[22:23]
	v_max3_f32 v81, v81, v121, v140
	v_max3_f32 v82, v82, v142, v143
	s_add_u32 s35, s20, s24
	v_max3_f32 v81, v81, v141, v124
	v_max3_f32 v82, v82, v126, v127
	s_addc_u32 s36, s21, s19
	v_add_f32_e32 v251, v251, v80
	v_max3_f32 v80, v81, v125, v82
	s_add_u32 s22, s35, 0x9ac1000
	v_mov_b32_e32 v81, v80
	s_addc_u32 s23, s36, 0
	s_lshl_b32 s34, s31, 1
	v_permlane32_swap_b32_e32 v80, v81
	s_add_i32 s34, s34, s29
	v_max_f32_e32 v81, v81, v81
	v_max_f32_e32 v80, v80, v80
	s_mov_b32 m0, s34
	s_nop 0
	global_load_lds_dwordx4 v242, s[22:23]
	s_add_u32 s22, s35, 0x9ac1080
	v_max_f32_e32 v80, v80, v81
	s_addc_u32 s23, s36, 0
	s_addk_i32 s34, 0x2000
	s_mov_b32 m0, s34
	s_nop 0
	global_load_lds_dwordx4 v242, s[22:23]
	v_cmp_lt_f32_e32 vcc, s25, v80
	s_cmp_lg_u64 vcc, 0
	s_cselect_b64 s[22:23], -1, 0
	s_cbranch_vccnz .LBB0_485

.LBB0_480:
	s_add_i32 s22, s31, 0x2000
	s_cmpk_lg_i32 s31, 0x4000
	s_cselect_b32 s34, s22, 0
	s_lshl_b32 s22, s33, 1
	v_add_u32_e32 v236, s22, v245
	ds_read_b64_tr_b16 v[212:213], v236 offset:24576
	ds_read_b64_tr_b16 v[214:215], v236 offset:25088
	v_mfma_f32_32x32x16_bf16 v[96:111], v[80:83], v[172:175], v[64:79]
	v_add_f32_e32 v84, v128, v129
	v_add_f32_e32 v84, v130, v84
	v_add_f32_e32 v84, v131, v84
	v_add_f32_e32 v84, v132, v84
	v_add_f32_e32 v84, v133, v84
	v_cvt_pk_bf16_f32 v156, v128, v129
	v_cvt_pk_bf16_f32 v157, v130, v131
	ds_read_b64_tr_b16 v[204:205], v236 offset:28672
	ds_read_b64_tr_b16 v[206:207], v236 offset:29184
	v_add_f32_e32 v80, v134, v84
	v_add_f32_e32 v80, v135, v80
	v_add_f32_e32 v80, v136, v80
	v_add_f32_e32 v128, v137, v80
	v_mfma_f32_32x32x16_bf16 v[80:95], v[196:199], v[172:175], v[64:79]
	v_cvt_pk_bf16_f32 v158, v132, v133
	v_cvt_pk_bf16_f32 v159, v134, v135
	ds_read_b64_tr_b16 v[208:209], v236 offset:25600
	ds_read_b64_tr_b16 v[210:211], v236 offset:26112
	v_mfma_f32_32x32x16_bf16 v[96:111], v[200:203], v[168:171], v[96:111]
	v_add_f32_e32 v128, v138, v128
	v_add_f32_e32 v128, v139, v128
	v_add_f32_e32 v128, v140, v128
	v_add_f32_e32 v128, v141, v128
	v_cvt_pk_bf16_f32 v152, v136, v137
	v_cvt_pk_bf16_f32 v153, v138, v139
	ds_read_b64_tr_b16 v[132:133], v236 offset:29696
	ds_read_b64_tr_b16 v[134:135], v236 offset:30208
	v_mfma_f32_32x32x16_bf16 v[80:95], v[192:195], v[168:171], v[80:95]
	v_add_f32_e32 v128, v142, v128
	v_add_f32_e32 v128, v143, v128
	v_add_f32_e32 v128, v112, v128
	v_add_f32_e32 v136, v113, v128
	v_cvt_pk_bf16_f32 v154, v140, v141
	v_cvt_pk_bf16_f32 v155, v142, v143
	ds_read_b64_tr_b16 v[128:129], v236 offset:26624
	ds_read_b64_tr_b16 v[130:131], v236 offset:27136
	v_mfma_f32_32x32x16_bf16 v[96:111], v[188:191], v[164:167], v[96:111]
	v_add_f32_e32 v136, v114, v136
	v_add_f32_e32 v136, v115, v136
	v_add_f32_e32 v136, v116, v136
	v_add_f32_e32 v136, v117, v136
	v_cvt_pk_bf16_f32 v148, v112, v113
	v_cvt_pk_bf16_f32 v149, v114, v115
	ds_read_b64_tr_b16 v[112:113], v236 offset:30720
	ds_read_b64_tr_b16 v[114:115], v236 offset:31232
	v_mfma_f32_32x32x16_bf16 v[80:95], v[184:187], v[164:167], v[80:95]
	v_add_f32_e32 v136, v118, v136
	v_add_f32_e32 v136, v119, v136
	v_add_f32_e32 v136, v120, v136
	v_add_f32_e32 v136, v121, v136
	v_cvt_pk_bf16_f32 v150, v116, v117
	v_cvt_pk_bf16_f32 v151, v118, v119
	ds_read_b64_tr_b16 v[116:117], v236 offset:27648
	ds_read_b64_tr_b16 v[118:119], v236 offset:28160
	v_mfma_f32_32x32x16_bf16 v[96:111], v[180:183], v[160:163], v[96:111]
	v_add_f32_e32 v136, v122, v136
	v_add_f32_e32 v136, v123, v136
	v_add_f32_e32 v136, v124, v136
	v_add_f32_e32 v136, v125, v136
	v_cvt_pk_bf16_f32 v144, v120, v121
	v_cvt_pk_bf16_f32 v145, v122, v123
	ds_read_b64_tr_b16 v[120:121], v236 offset:31744
	ds_read_b64_tr_b16 v[122:123], v236 offset:32256
	v_mfma_f32_32x32x16_bf16 v[80:95], v[176:179], v[160:163], v[80:95]
	v_add_f32_e32 v136, v126, v136
	v_add_f32_e32 v136, v127, v136
	v_cvt_pk_bf16_f32 v146, v124, v125
	v_cvt_pk_bf16_f32 v147, v126, v127
	v_max_f32_e32 v124, v97, v97
	v_max_f32_e32 v125, v96, v96
	v_max_f32_e32 v124, v125, v124
	s_nop 3
	v_max3_f32 v125, v98, v99, v81
	v_max3_f32 v124, v124, v80, v82
	v_max3_f32 v124, v124, v83, v100
	v_max3_f32 v125, v125, v102, v103
	v_max3_f32 v124, v124, v101, v84
	v_max3_f32 v125, v125, v86, v87
	v_max3_f32 v124, v124, v85, v104
	v_max3_f32 v125, v125, v106, v107
	v_max3_f32 v124, v124, v105, v88
	v_max3_f32 v125, v125, v90, v91
	v_max3_f32 v124, v124, v89, v108
	v_max3_f32 v125, v125, v110, v111
	s_add_u32 s22, s37, 0x9be0800
	v_max3_f32 v124, v124, v109, v92
	v_max3_f32 v125, v125, v94, v95
	s_addc_u32 s23, s39, 0
	s_add_i32 s33, s31, s28
	v_max3_f32 v124, v124, v93, v125
	s_mov_b32 m0, s33
	s_nop 0
	global_load_lds_dwordx4 v241, s[22:23]
	s_add_u32 s22, s35, 0x9b21000
	v_mov_b32_e32 v125, v124
	s_addc_u32 s23, s36, 0
	s_lshl_b32 s33, s34, 1
	v_permlane32_swap_b32_e32 v124, v125
	s_add_i32 s33, s33, s29
	v_max_f32_e32 v125, v125, v125
	v_max_f32_e32 v124, v124, v124
	s_mov_b32 m0, s33
	s_nop 0
	global_load_lds_dwordx4 v242, s[22:23]
	s_add_u32 s22, s35, 0x9b21080
	v_max_f32_e32 v124, v124, v125
	s_addc_u32 s23, s36, 0
	s_addk_i32 s33, 0x2000
	s_mov_b32 m0, s33
	s_nop 0
	global_load_lds_dwordx4 v242, s[22:23]
	v_cmp_lt_f32_e32 vcc, s25, v124
	s_cmp_lg_u64 vcc, 0
	v_add_f32_e32 v251, v251, v136
	s_cselect_b64 s[22:23], -1, 0
	s_cbranch_vccnz .LBB0_488

; #define WAIT_BAR(N) asm volatile("s_waitcnt vmcnt(" #N ") lgkmcnt(0)\n\ts_barrier" ::: "memory")
;   #define RESC() do { if constexpr (!NOMAX) if (resc) { asm volatile("s_waitcnt lgkmcnt(0)" ::: "memory"); \
;       _Pragma("unroll") for (int d_ = 0; d_ < 2 * DV2; ++d_) _Pragma("unroll") for (int r = 0; r < 16; ++r) o[d_][r] *= wsf[crow(r, hi)]; } } while (0)
;   #define ROT() do { sl_prev = sl_cur; sl_cur = sl_next; sl_next = (sl_next == (NSLOT - 1) * SLOTB) ? 0 : sl_next + SLOTB; } while (0)
;     ...
;   int t = 1;
;   for (; t + 5 < NT; t += 2) {
;     STEP(pB0, pB1, pA0, pA1, t, true, true, true);     if constexpr (DV2 == 2) { WAIT_BAR(3); } else { WAIT_BAR(2); } RESC(); ROT();
;     STEP(pA0, pA1, pB0, pB1, t + 1, true, true, true); if constexpr (DV2 == 2) { WAIT_BAR(3); } else { WAIT_BAR(2); } RESC(); ROT();
.LBB0_970:
	v_add_u32_e32 v65, s31, v189
	ds_read_b64_tr_b16 v[178:179], v65 offset:24576
	ds_read_b64_tr_b16 v[180:181], v65 offset:25088
	v_add_f32_e32 v86, v66, v67
	v_add_f32_e32 v86, v68, v86
	v_add_f32_e32 v86, v69, v86
	v_add_f32_e32 v86, v70, v86
	v_add_f32_e32 v86, v71, v86
	v_cvt_pk_bf16_f32 v142, v66, v67
	v_cvt_pk_bf16_f32 v143, v68, v69
	v_mfma_f32_32x32x16_bf16 v[98:113], v[82:85], v[158:161], v[32:47]
	ds_read_b64_tr_b16 v[174:175], v65 offset:28672
	ds_read_b64_tr_b16 v[176:177], v65 offset:29184
	v_add_f32_e32 v66, v72, v86
	v_mfma_f32_32x32x16_bf16 v[82:97], v[166:169], v[158:161], v[32:47]
	v_add_f32_e32 v66, v73, v66
	v_add_f32_e32 v66, v74, v66
	v_add_f32_e32 v130, v75, v66
	v_cvt_pk_bf16_f32 v144, v70, v71
	v_cvt_pk_bf16_f32 v145, v72, v73
	ds_read_b64_tr_b16 v[66:67], v65 offset:25600
	ds_read_b64_tr_b16 v[68:69], v65 offset:26112
	v_add_f32_e32 v70, v76, v130
	v_add_f32_e32 v70, v77, v70
	v_add_f32_e32 v70, v78, v70
	v_add_f32_e32 v130, v79, v70
	v_cvt_pk_bf16_f32 v138, v74, v75
	v_cvt_pk_bf16_f32 v139, v76, v77
	v_mfma_f32_32x32x16_bf16 v[98:113], v[170:173], v[154:157], v[98:113]
	ds_read_b64_tr_b16 v[70:71], v65 offset:29696
	ds_read_b64_tr_b16 v[72:73], v65 offset:30208
	v_mfma_f32_32x32x16_bf16 v[82:97], v[162:165], v[154:157], v[82:97]
	v_add_f32_e32 v74, v80, v130
	v_add_f32_e32 v74, v81, v74
	v_add_f32_e32 v74, v48, v74
	v_add_f32_e32 v130, v49, v74
	v_cvt_pk_bf16_f32 v140, v78, v79
	v_cvt_pk_bf16_f32 v141, v80, v81
	ds_read_b64_tr_b16 v[74:75], v65 offset:26624
	ds_read_b64_tr_b16 v[76:77], v65 offset:27136
	v_add_f32_e32 v78, v50, v130
	v_add_f32_e32 v78, v51, v78
	v_add_f32_e32 v78, v52, v78
	v_add_f32_e32 v78, v53, v78
	v_cvt_pk_bf16_f32 v134, v48, v49
	v_cvt_pk_bf16_f32 v135, v50, v51
	v_mfma_f32_32x32x16_bf16 v[98:113], v[126:129], v[150:153], v[98:113]
	ds_read_b64_tr_b16 v[48:49], v65 offset:30720
	ds_read_b64_tr_b16 v[50:51], v65 offset:31232
	v_mfma_f32_32x32x16_bf16 v[82:97], v[122:125], v[150:153], v[82:97]
	v_add_f32_e32 v78, v54, v78
	v_add_f32_e32 v78, v55, v78
	v_add_f32_e32 v78, v56, v78
	v_add_f32_e32 v78, v57, v78
	v_cvt_pk_bf16_f32 v136, v52, v53
	v_cvt_pk_bf16_f32 v137, v54, v55
	ds_read_b64_tr_b16 v[52:53], v65 offset:27648
	ds_read_b64_tr_b16 v[54:55], v65 offset:28160
	v_add_f32_e32 v78, v58, v78
	v_add_f32_e32 v78, v59, v78
	v_add_f32_e32 v78, v60, v78
	v_add_f32_e32 v78, v61, v78
	v_cvt_pk_bf16_f32 v130, v56, v57
	v_cvt_pk_bf16_f32 v131, v58, v59
	v_mfma_f32_32x32x16_bf16 v[98:113], v[118:121], v[146:149], v[98:113]
	ds_read_b64_tr_b16 v[56:57], v65 offset:31744
	ds_read_b64_tr_b16 v[58:59], v65 offset:32256
	v_mfma_f32_32x32x16_bf16 v[82:97], v[114:117], v[146:149], v[82:97]
	v_add_f32_e32 v65, v62, v78
	v_add_f32_e32 v65, v63, v65
	v_cvt_pk_bf16_f32 v132, v60, v61
	v_cvt_pk_bf16_f32 v133, v62, v63
	s_add_u32 s31, s16, s22
	s_addc_u32 s33, s17, 0
	s_add_i32 m0, s29, s18
	s_add_u32 s34, s31, 0x9ac0800
	s_addc_u32 s35, s33, 0
	global_load_lds_dwordx4 v184, s[34:35]
	s_add_u32 s34, s20, s22
	s_addc_u32 s35, s21, 0
	s_add_i32 m0, s28, s15
	s_add_u32 s36, s34, 0x9a60a00
	s_addc_u32 s37, s35, 0
	global_load_lds_dwordx4 v185, s[36:37]
	v_add_f32_e32 v64, v64, v65
	s_waitcnt lgkmcnt(0)
	v_mfma_f32_32x32x16_bf16 v[0:15], v[142:145], v[178:181], v[0:15]
	v_exp_f32_e32 v98, v98
	v_exp_f32_e32 v99, v99
	v_exp_f32_e32 v100, v100
	v_exp_f32_e32 v101, v101
	v_mfma_f32_32x32x16_bf16 v[16:31], v[142:145], v[174:177], v[16:31]
	v_exp_f32_e32 v102, v102
	v_exp_f32_e32 v103, v103
	v_exp_f32_e32 v104, v104
	v_exp_f32_e32 v105, v105
	v_add_u32_e32 v65, s28, v187
	ds_read_b128 v[60:63], v65
	ds_read_b128 v[118:121], v65 offset:512
	v_mfma_f32_32x32x16_bf16 v[0:15], v[138:141], v[66:69], v[0:15]
	v_exp_f32_e32 v106, v106
	v_exp_f32_e32 v107, v107
	v_exp_f32_e32 v108, v108
	v_exp_f32_e32 v109, v109
	ds_read_b128 v[122:125], v65 offset:2048
	ds_read_b128 v[126:129], v65 offset:2560
	v_mfma_f32_32x32x16_bf16 v[16:31], v[138:141], v[70:73], v[16:31]
	v_exp_f32_e32 v110, v110
	v_exp_f32_e32 v111, v111
	v_exp_f32_e32 v112, v112
	v_exp_f32_e32 v113, v113
	ds_read_b128 v[162:165], v65 offset:4096
	ds_read_b128 v[166:169], v65 offset:4608
	v_mfma_f32_32x32x16_bf16 v[0:15], v[134:137], v[74:77], v[0:15]
	v_exp_f32_e32 v82, v82
	v_exp_f32_e32 v83, v83
	v_exp_f32_e32 v84, v84
	v_exp_f32_e32 v85, v85
	ds_read_b128 v[170:173], v65 offset:6144
	ds_read_b128 v[114:117], v65 offset:6656
	v_mfma_f32_32x32x16_bf16 v[16:31], v[134:137], v[48:51], v[16:31]
	v_exp_f32_e32 v86, v86
	v_exp_f32_e32 v87, v87
	v_exp_f32_e32 v88, v88
	v_exp_f32_e32 v89, v89
	v_mfma_f32_32x32x16_bf16 v[0:15], v[130:133], v[52:55], v[0:15]
	v_exp_f32_e32 v90, v90
	v_exp_f32_e32 v91, v91
	v_exp_f32_e32 v92, v92
	v_exp_f32_e32 v93, v93
	v_mfma_f32_32x32x16_bf16 v[16:31], v[130:133], v[56:59], v[16:31]
	v_exp_f32_e32 v94, v94
	v_exp_f32_e32 v95, v95
	v_exp_f32_e32 v96, v96
	v_exp_f32_e32 v97, v97
	s_waitcnt vmcnt(2) lgkmcnt(0)
	s_barrier
; #define WAIT_BAR(N) asm volatile("s_waitcnt vmcnt(" #N ") lgkmcnt(0)\n\ts_barrier" ::: "memory")
;   #define RESC() do { if constexpr (!NOMAX) if (resc) { asm volatile("s_waitcnt lgkmcnt(0)" ::: "memory"); \
;       _Pragma("unroll") for (int d_ = 0; d_ < 2 * DV2; ++d_) _Pragma("unroll") for (int r = 0; r < 16; ++r) o[d_][r] *= wsf[crow(r, hi)]; } } while (0)
;   #define ROT() do { sl_prev = sl_cur; sl_cur = sl_next; sl_next = (sl_next == (NSLOT - 1) * SLOTB) ? 0 : sl_next + SLOTB; } while (0)
;     ...
;   int t = 1;
;   for (; t + 5 < NT; t += 2) {
;     STEP(pB0, pB1, pA0, pA1, t, true, true, true);     if constexpr (DV2 == 2) { WAIT_BAR(3); } else { WAIT_BAR(2); } RESC(); ROT();
;     STEP(pA0, pA1, pB0, pB1, t + 1, true, true, true); if constexpr (DV2 == 2) { WAIT_BAR(3); } else { WAIT_BAR(2); } RESC(); ROT();
	s_add_i32 s30, s28, 0x2000
	s_cmpk_lg_i32 s28, 0x4000
	s_cselect_b32 s30, s30, 0
	v_add_u32_e32 v65, s29, v189
	ds_read_b64_tr_b16 v[174:175], v65 offset:24576
	ds_read_b64_tr_b16 v[176:177], v65 offset:25088
	v_mfma_f32_32x32x16_bf16 v[66:81], v[60:63], v[158:161], v[32:47]
	v_add_f32_e32 v48, v98, v99
	v_add_f32_e32 v48, v100, v48
	v_add_f32_e32 v48, v101, v48
	v_add_f32_e32 v48, v102, v48
	v_add_f32_e32 v48, v103, v48
	v_cvt_pk_bf16_f32 v142, v98, v99
	v_cvt_pk_bf16_f32 v143, v100, v101
	ds_read_b64_tr_b16 v[178:179], v65 offset:28672
	ds_read_b64_tr_b16 v[180:181], v65 offset:29184
	v_add_f32_e32 v48, v104, v48
	v_add_f32_e32 v48, v105, v48
	v_add_f32_e32 v48, v106, v48
	v_add_f32_e32 v130, v107, v48
	v_mfma_f32_32x32x16_bf16 v[48:63], v[118:121], v[158:161], v[32:47]
	v_cvt_pk_bf16_f32 v144, v102, v103
	v_cvt_pk_bf16_f32 v145, v104, v105
	ds_read_b64_tr_b16 v[98:99], v65 offset:25600
	ds_read_b64_tr_b16 v[100:101], v65 offset:26112
	v_mfma_f32_32x32x16_bf16 v[66:81], v[122:125], v[154:157], v[66:81]
	v_add_f32_e32 v102, v108, v130
	v_add_f32_e32 v102, v109, v102
	v_add_f32_e32 v102, v110, v102
	v_add_f32_e32 v118, v111, v102
	v_cvt_pk_bf16_f32 v138, v106, v107
	v_cvt_pk_bf16_f32 v139, v108, v109
	ds_read_b64_tr_b16 v[102:103], v65 offset:29696
	ds_read_b64_tr_b16 v[104:105], v65 offset:30208
	v_mfma_f32_32x32x16_bf16 v[48:63], v[126:129], v[154:157], v[48:63]
	v_add_f32_e32 v106, v112, v118
	v_add_f32_e32 v106, v113, v106
	v_add_f32_e32 v106, v82, v106
	v_add_f32_e32 v118, v83, v106
	v_cvt_pk_bf16_f32 v140, v110, v111
	v_cvt_pk_bf16_f32 v141, v112, v113
	ds_read_b64_tr_b16 v[106:107], v65 offset:26624
	ds_read_b64_tr_b16 v[108:109], v65 offset:27136
	v_mfma_f32_32x32x16_bf16 v[66:81], v[162:165], v[150:153], v[66:81]
	v_add_f32_e32 v110, v84, v118
	v_add_f32_e32 v110, v85, v110
	v_add_f32_e32 v110, v86, v110
	v_add_f32_e32 v118, v87, v110
	v_cvt_pk_bf16_f32 v134, v82, v83
	v_cvt_pk_bf16_f32 v135, v84, v85
	ds_read_b64_tr_b16 v[110:111], v65 offset:30720
	ds_read_b64_tr_b16 v[112:113], v65 offset:31232
	v_mfma_f32_32x32x16_bf16 v[48:63], v[166:169], v[150:153], v[48:63]
	v_add_f32_e32 v82, v88, v118
	v_add_f32_e32 v82, v89, v82
	v_add_f32_e32 v82, v90, v82
	v_add_f32_e32 v82, v91, v82
	v_cvt_pk_bf16_f32 v136, v86, v87
	v_cvt_pk_bf16_f32 v137, v88, v89
	ds_read_b64_tr_b16 v[86:87], v65 offset:27648
	ds_read_b64_tr_b16 v[88:89], v65 offset:28160
	v_mfma_f32_32x32x16_bf16 v[66:81], v[170:173], v[146:149], v[66:81]
	v_add_f32_e32 v82, v92, v82
	v_add_f32_e32 v82, v93, v82
	v_add_f32_e32 v82, v94, v82
	v_add_f32_e32 v82, v95, v82
	v_cvt_pk_bf16_f32 v130, v90, v91
	v_cvt_pk_bf16_f32 v131, v92, v93
	ds_read_b64_tr_b16 v[90:91], v65 offset:31744
	ds_read_b64_tr_b16 v[92:93], v65 offset:32256
	v_mfma_f32_32x32x16_bf16 v[48:63], v[114:117], v[146:149], v[48:63]
	v_add_f32_e32 v65, v96, v82
	v_add_f32_e32 v65, v97, v65
	v_cvt_pk_bf16_f32 v132, v94, v95
	v_cvt_pk_bf16_f32 v133, v96, v97
	s_add_i32 m0, s28, s18
	s_add_u32 s36, s31, 0x9af0800
	s_addc_u32 s37, s33, 0
	global_load_lds_dwordx4 v184, s[36:37]
	s_add_i32 m0, s30, s15
	s_add_u32 s34, s34, 0x9a90a00
	s_addc_u32 s35, s35, 0
	global_load_lds_dwordx4 v185, s[34:35]
	v_add_f32_e32 v64, v64, v65
	s_waitcnt lgkmcnt(0)
	v_mfma_f32_32x32x16_bf16 v[0:15], v[142:145], v[174:177], v[0:15]
	v_exp_f32_e32 v66, v66
	v_exp_f32_e32 v67, v67
	v_exp_f32_e32 v68, v68
	v_exp_f32_e32 v69, v69
	v_mfma_f32_32x32x16_bf16 v[16:31], v[142:145], v[178:181], v[16:31]
	v_exp_f32_e32 v70, v70
	v_exp_f32_e32 v71, v71
	v_exp_f32_e32 v72, v72
	v_exp_f32_e32 v73, v73
	v_add_u32_e32 v65, s30, v187
	ds_read_b128 v[82:85], v65
	ds_read_b128 v[166:169], v65 offset:512
	v_mfma_f32_32x32x16_bf16 v[0:15], v[138:141], v[98:101], v[0:15]
	v_exp_f32_e32 v74, v74
	v_exp_f32_e32 v75, v75
	v_exp_f32_e32 v76, v76
	v_exp_f32_e32 v77, v77
	ds_read_b128 v[170:173], v65 offset:2048
	ds_read_b128 v[162:165], v65 offset:2560
	v_mfma_f32_32x32x16_bf16 v[16:31], v[138:141], v[102:105], v[16:31]
	v_exp_f32_e32 v78, v78
	v_exp_f32_e32 v79, v79
	v_exp_f32_e32 v80, v80
	v_exp_f32_e32 v81, v81
	ds_read_b128 v[126:129], v65 offset:4096
	ds_read_b128 v[122:125], v65 offset:4608
	v_mfma_f32_32x32x16_bf16 v[0:15], v[134:137], v[106:109], v[0:15]
	v_exp_f32_e32 v48, v48
	v_exp_f32_e32 v49, v49
	v_exp_f32_e32 v50, v50
	v_exp_f32_e32 v51, v51
	ds_read_b128 v[118:121], v65 offset:6144
	ds_read_b128 v[114:117], v65 offset:6656
	v_mfma_f32_32x32x16_bf16 v[16:31], v[134:137], v[110:113], v[16:31]
	v_exp_f32_e32 v52, v52
	v_exp_f32_e32 v53, v53
	v_exp_f32_e32 v54, v54
	v_exp_f32_e32 v55, v55
	v_mfma_f32_32x32x16_bf16 v[0:15], v[130:133], v[86:89], v[0:15]
	v_exp_f32_e32 v56, v56
	v_exp_f32_e32 v57, v57
	v_exp_f32_e32 v58, v58
	v_exp_f32_e32 v59, v59
	v_mfma_f32_32x32x16_bf16 v[16:31], v[130:133], v[90:93], v[16:31]
	v_exp_f32_e32 v60, v60
	v_exp_f32_e32 v61, v61
	v_exp_f32_e32 v62, v62
	v_exp_f32_e32 v63, v63
	s_add_i32 s33, s30, 0x2000
	s_cmpk_lg_i32 s30, 0x4000
	s_mov_b32 s31, s28
	s_cselect_b32 s28, s33, 0
	s_add_i32 s24, s24, 2
	s_add_u32 s20, s20, 0x60000
	s_addc_u32 s21, s21, 0
	s_waitcnt vmcnt(2) lgkmcnt(0)
	s_barrier
	s_add_u32 s16, s16, 0x60000
	s_addc_u32 s17, s17, 0
	s_mov_b32 s29, s30
	s_cmp_gt_u32 s24, 56
	s_cbranch_scc0 .LBB0_970
; #define WAIT_BAR(N) asm volatile("s_waitcnt vmcnt(" #N ") lgkmcnt(0)\n\ts_barrier" ::: "memory")
;   #define RESC() do { if constexpr (!NOMAX) if (resc) { asm volatile("s_waitcnt lgkmcnt(0)" ::: "memory"); \
;       _Pragma("unroll") for (int d_ = 0; d_ < 2 * DV2; ++d_) _Pragma("unroll") for (int r = 0; r < 16; ++r) o[d_][r] *= wsf[crow(r, hi)]; } } while (0)
;   #define ROT() do { sl_prev = sl_cur; sl_cur = sl_next; sl_next = (sl_next == (NSLOT - 1) * SLOTB) ? 0 : sl_next + SLOTB; } while (0)
;   #define ENDW(tt) do { if constexpr (DV2 == 2) { if ((tt) + 3 < NT) { WAIT_BAR(3); } else if ((tt) + 2 < NT) { WAIT_BAR(2); } else { WAIT_BAR(0); } } \
;     else { if ((tt) + 3 < NT) { WAIT_BAR(2); } else if ((tt) + 2 < NT) { WAIT_BAR(1); } else { WAIT_BAR(0); } } } while (0)
;     ...
;   int t = 1;
;   for (; t + 5 < NT; t += 2) {
;     STEP(pB0, pB1, pA0, pA1, t, true, true, true);     if constexpr (DV2 == 2) { WAIT_BAR(3); } else { WAIT_BAR(2); } RESC(); ROT();
;     STEP(pA0, pA1, pB0, pB1, t + 1, true, true, true); if constexpr (DV2 == 2) { WAIT_BAR(3); } else { WAIT_BAR(2); } RESC(); ROT();
;   }
;     ...
;   for (; t + 1 < NT; t += 2) {
;     STEP(pB0, pB1, pA0, pA1, t, (t + 3 < NT), (t + 1 < NT), (t + 1 < NT));         ENDW(t);     RESC(); ROT();
;     STEP(pA0, pA1, pB0, pB1, t + 1, (t + 4 < NT), (t + 2 < NT), (t + 2 < NT));     ENDW(t + 1); RESC(); ROT();
	s_and_b32 s16, s23, 0x3fffffc0
	s_lshl_b32 s16, s16, 2
	s_add_i32 s16, s16, 0
	ds_read_b64_tr_b16 v[174:175], v189 offset:32768
	ds_read_b64_tr_b16 v[176:177], v189 offset:33280
	v_add_f32_e32 v65, v66, v67
	v_add_f32_e32 v65, v68, v65
	v_add_f32_e32 v65, v69, v65
	v_add_f32_e32 v65, v70, v65
	v_add_f32_e32 v65, v71, v65
	v_cvt_pk_bf16_f32 v142, v66, v67
	v_cvt_pk_bf16_f32 v143, v68, v69
	s_waitcnt lgkmcnt(9)
	v_mfma_f32_32x32x16_bf16 v[98:113], v[82:85], v[158:161], v[32:47]
	ds_read_b64_tr_b16 v[178:179], v189 offset:36864
	ds_read_b64_tr_b16 v[180:181], v189 offset:37376
	v_add_f32_e32 v65, v72, v65
	v_add_f32_e32 v65, v73, v65
	v_add_f32_e32 v65, v74, v65
	v_add_f32_e32 v65, v75, v65
	v_cvt_pk_bf16_f32 v144, v70, v71
	v_cvt_pk_bf16_f32 v145, v72, v73
	s_waitcnt lgkmcnt(10)
	v_mfma_f32_32x32x16_bf16 v[82:97], v[166:169], v[158:161], v[32:47]
	ds_read_b64_tr_b16 v[66:67], v189 offset:33792
	ds_read_b64_tr_b16 v[68:69], v189 offset:34304
	v_add_f32_e32 v65, v76, v65
	v_add_f32_e32 v65, v77, v65
	v_add_f32_e32 v65, v78, v65
	v_add_f32_e32 v65, v79, v65
	v_cvt_pk_bf16_f32 v138, v74, v75
	v_cvt_pk_bf16_f32 v139, v76, v77
	s_waitcnt lgkmcnt(11)
	v_mfma_f32_32x32x16_bf16 v[98:113], v[170:173], v[154:157], v[98:113]
	ds_read_b64_tr_b16 v[70:71], v189 offset:37888
	ds_read_b64_tr_b16 v[72:73], v189 offset:38400
	v_add_f32_e32 v65, v80, v65
	v_add_f32_e32 v65, v81, v65
	v_add_f32_e32 v65, v48, v65
	v_add_f32_e32 v65, v49, v65
	v_cvt_pk_bf16_f32 v140, v78, v79
	v_cvt_pk_bf16_f32 v141, v80, v81
	s_waitcnt lgkmcnt(12)
	v_mfma_f32_32x32x16_bf16 v[82:97], v[162:165], v[154:157], v[82:97]
	ds_read_b64_tr_b16 v[74:75], v189 offset:34816
	ds_read_b64_tr_b16 v[76:77], v189 offset:35328
	v_add_f32_e32 v65, v50, v65
	v_add_f32_e32 v65, v51, v65
	v_add_f32_e32 v65, v52, v65
	v_add_f32_e32 v65, v53, v65
	v_cvt_pk_bf16_f32 v134, v48, v49
	v_cvt_pk_bf16_f32 v135, v50, v51
	s_waitcnt lgkmcnt(13)
	v_mfma_f32_32x32x16_bf16 v[98:113], v[126:129], v[150:153], v[98:113]
	ds_read_b64_tr_b16 v[48:49], v189 offset:38912
	ds_read_b64_tr_b16 v[50:51], v189 offset:39424
	v_add_f32_e32 v65, v54, v65
	v_add_f32_e32 v65, v55, v65
	v_add_f32_e32 v65, v56, v65
	v_add_f32_e32 v65, v57, v65
	v_cvt_pk_bf16_f32 v136, v52, v53
	v_cvt_pk_bf16_f32 v137, v54, v55
	s_waitcnt lgkmcnt(14)
	v_mfma_f32_32x32x16_bf16 v[82:97], v[122:125], v[150:153], v[82:97]
	ds_read_b64_tr_b16 v[52:53], v189 offset:35840
	ds_read_b64_tr_b16 v[54:55], v189 offset:36352
	v_add_f32_e32 v65, v58, v65
	v_add_f32_e32 v65, v59, v65
	v_add_f32_e32 v65, v60, v65
	v_add_f32_e32 v65, v61, v65
	v_cvt_pk_bf16_f32 v130, v56, v57
	v_cvt_pk_bf16_f32 v131, v58, v59
	s_waitcnt lgkmcnt(14)
	v_mfma_f32_32x32x16_bf16 v[98:113], v[118:121], v[146:149], v[98:113]
	ds_read_b64_tr_b16 v[56:57], v189 offset:39936
	ds_read_b64_tr_b16 v[58:59], v189 offset:40448
	v_add_f32_e32 v65, v62, v65
	v_add_f32_e32 v65, v63, v65
	v_add_f32_e32 v65, 0, v65
	v_cvt_pk_bf16_f32 v132, v60, v61
	v_cvt_pk_bf16_f32 v133, v62, v63
	v_mfma_f32_32x32x16_bf16 v[82:97], v[114:117], v[146:149], v[82:97]
	s_add_u32 s20, s10, 0xba0000
	s_addc_u32 s21, s11, 0
	s_cmp_lg_u32 0, -1
	s_cselect_b32 s17, 0, 0
	s_add_i32 s17, s17, s19
	s_add_i32 s19, s17, 0x4000
	s_mov_b32 s22, m0
	s_mov_b32 m0, s19
	s_nop 0
	global_load_lds_dwordx4 v184, s[20:21]
	s_mov_b32 m0, s22
	s_add_u32 s20, s8, 0xb40000
	s_addc_u32 s21, s9, 0
	s_mov_b32 s19, m0
	s_mov_b32 m0, s15
	s_nop 0
	global_load_lds_dwordx4 v185, s[20:21]
	s_mov_b32 m0, s19
	v_add_f32_e32 v183, v64, v65
	s_waitcnt lgkmcnt(14)
	v_mfma_f32_32x32x16_bf16 v[0:15], v[142:145], v[174:177], v[0:15]
	v_exp_f32_e32 v98, v98
	v_exp_f32_e32 v99, v99
	v_exp_f32_e32 v100, v100
	v_exp_f32_e32 v101, v101
	s_waitcnt lgkmcnt(12)
	v_mfma_f32_32x32x16_bf16 v[16:31], v[142:145], v[178:181], v[16:31]
	v_exp_f32_e32 v102, v102
	v_exp_f32_e32 v103, v103
	v_exp_f32_e32 v104, v104
	v_exp_f32_e32 v105, v105
	ds_read_b128 v[60:63], v187
	ds_read_b128 v[78:81], v187 offset:512
	s_waitcnt lgkmcnt(12)
	v_mfma_f32_32x32x16_bf16 v[0:15], v[138:141], v[66:69], v[0:15]
	v_exp_f32_e32 v106, v106
	v_exp_f32_e32 v107, v107
	v_exp_f32_e32 v108, v108
	v_exp_f32_e32 v109, v109
	ds_read_b128 v[162:165], v187 offset:2048
	ds_read_b128 v[166:169], v187 offset:2560
	s_waitcnt lgkmcnt(12)
	v_mfma_f32_32x32x16_bf16 v[16:31], v[138:141], v[70:73], v[16:31]
	v_exp_f32_e32 v110, v110
	v_exp_f32_e32 v111, v111
	v_exp_f32_e32 v112, v112
	v_exp_f32_e32 v113, v113
	ds_read_b128 v[68:71], v187 offset:4096
	ds_read_b128 v[170:173], v187 offset:4608
	s_waitcnt lgkmcnt(12)
	v_mfma_f32_32x32x16_bf16 v[0:15], v[134:137], v[74:77], v[0:15]
	v_exp_f32_e32 v82, v82
	v_exp_f32_e32 v83, v83
	v_exp_f32_e32 v84, v84
	v_exp_f32_e32 v85, v85
	ds_read_b128 v[72:75], v187 offset:6144
	ds_read_b128 v[64:67], v187 offset:6656
	s_waitcnt lgkmcnt(12)
	v_mfma_f32_32x32x16_bf16 v[16:31], v[134:137], v[48:51], v[16:31]
	v_exp_f32_e32 v86, v86
	v_exp_f32_e32 v87, v87
	v_exp_f32_e32 v88, v88
	v_exp_f32_e32 v89, v89
	s_waitcnt lgkmcnt(10)
	v_mfma_f32_32x32x16_bf16 v[0:15], v[130:133], v[52:55], v[0:15]
	v_exp_f32_e32 v90, v90
	v_exp_f32_e32 v91, v91
	v_exp_f32_e32 v92, v92
	v_exp_f32_e32 v93, v93
	s_waitcnt lgkmcnt(8)
	v_mfma_f32_32x32x16_bf16 v[16:31], v[130:133], v[56:59], v[16:31]
	v_exp_f32_e32 v94, v94
	v_exp_f32_e32 v95, v95
	v_exp_f32_e32 v96, v96
	v_exp_f32_e32 v97, v97
	s_waitcnt vmcnt(2) lgkmcnt(0)
	s_barrier
; #define WAIT_BAR(N) asm volatile("s_waitcnt vmcnt(" #N ") lgkmcnt(0)\n\ts_barrier" ::: "memory")
;   #define RESC() do { if constexpr (!NOMAX) if (resc) { asm volatile("s_waitcnt lgkmcnt(0)" ::: "memory"); \
;       _Pragma("unroll") for (int d_ = 0; d_ < 2 * DV2; ++d_) _Pragma("unroll") for (int r = 0; r < 16; ++r) o[d_][r] *= wsf[crow(r, hi)]; } } while (0)
;   #define ROT() do { sl_prev = sl_cur; sl_cur = sl_next; sl_next = (sl_next == (NSLOT - 1) * SLOTB) ? 0 : sl_next + SLOTB; } while (0)
;   #define ENDW(tt) do { if constexpr (DV2 == 2) { if ((tt) + 3 < NT) { WAIT_BAR(3); } else if ((tt) + 2 < NT) { WAIT_BAR(2); } else { WAIT_BAR(0); } } \
;     else { if ((tt) + 3 < NT) { WAIT_BAR(2); } else if ((tt) + 2 < NT) { WAIT_BAR(1); } else { WAIT_BAR(0); } } } while (0)
;     ...
;   int t = 1;
;   for (; t + 5 < NT; t += 2) {
;     STEP(pB0, pB1, pA0, pA1, t, true, true, true);     if constexpr (DV2 == 2) { WAIT_BAR(3); } else { WAIT_BAR(2); } RESC(); ROT();
;     STEP(pA0, pA1, pB0, pB1, t + 1, true, true, true); if constexpr (DV2 == 2) { WAIT_BAR(3); } else { WAIT_BAR(2); } RESC(); ROT();
;   }
;     ...
;   for (; t + 1 < NT; t += 2) {
;     STEP(pB0, pB1, pA0, pA1, t, (t + 3 < NT), (t + 1 < NT), (t + 1 < NT));         ENDW(t);     RESC(); ROT();
;     STEP(pA0, pA1, pB0, pB1, t + 1, (t + 4 < NT), (t + 2 < NT), (t + 2 < NT));     ENDW(t + 1); RESC(); ROT();
	ds_read_b64_tr_b16 v[174:175], v189 offset:40960
	ds_read_b64_tr_b16 v[176:177], v189 offset:41472
	v_add_f32_e32 v48, v98, v99
	v_add_f32_e32 v48, v100, v48
	v_add_f32_e32 v48, v101, v48
	v_add_f32_e32 v48, v102, v48
	v_add_f32_e32 v48, v103, v48
	v_cvt_pk_bf16_f32 v142, v98, v99
	v_cvt_pk_bf16_f32 v143, v100, v101
	s_waitcnt lgkmcnt(9)
	v_mfma_f32_32x32x16_bf16 v[114:129], v[60:63], v[158:161], v[32:47]
	ds_read_b64_tr_b16 v[98:99], v189 offset:45056
	ds_read_b64_tr_b16 v[100:101], v189 offset:45568
	v_add_f32_e32 v48, v104, v48
	v_add_f32_e32 v48, v105, v48
	v_add_f32_e32 v48, v106, v48
	v_add_f32_e32 v130, v107, v48
	s_waitcnt lgkmcnt(10)
	v_mfma_f32_32x32x16_bf16 v[48:63], v[78:81], v[158:161], v[32:47]
	v_cvt_pk_bf16_f32 v144, v102, v103
	v_cvt_pk_bf16_f32 v145, v104, v105
	ds_read_b64_tr_b16 v[76:77], v189 offset:41984
	ds_read_b64_tr_b16 v[78:79], v189 offset:42496
	v_add_f32_e32 v80, v108, v130
	v_add_f32_e32 v80, v109, v80
	v_add_f32_e32 v80, v110, v80
	v_add_f32_e32 v80, v111, v80
	v_cvt_pk_bf16_f32 v138, v106, v107
	v_cvt_pk_bf16_f32 v139, v108, v109
	s_waitcnt lgkmcnt(11)
	v_mfma_f32_32x32x16_bf16 v[114:129], v[162:165], v[154:157], v[114:129]
	ds_read_b64_tr_b16 v[102:103], v189 offset:46080
	ds_read_b64_tr_b16 v[104:105], v189 offset:46592
	s_waitcnt lgkmcnt(12)
	v_mfma_f32_32x32x16_bf16 v[48:63], v[166:169], v[154:157], v[48:63]
	v_add_f32_e32 v80, v112, v80
	v_add_f32_e32 v80, v113, v80
	v_add_f32_e32 v80, v82, v80
	v_add_f32_e32 v80, v83, v80
	v_cvt_pk_bf16_f32 v140, v110, v111
	v_cvt_pk_bf16_f32 v141, v112, v113
	ds_read_b64_tr_b16 v[106:107], v189 offset:43008
	ds_read_b64_tr_b16 v[108:109], v189 offset:43520
	s_waitcnt lgkmcnt(13)
	v_mfma_f32_32x32x16_bf16 v[114:129], v[68:71], v[150:153], v[114:129]
	v_add_f32_e32 v68, v84, v80
	v_add_f32_e32 v68, v85, v68
	v_add_f32_e32 v68, v86, v68
	v_add_f32_e32 v80, v87, v68
	v_cvt_pk_bf16_f32 v134, v82, v83
	v_cvt_pk_bf16_f32 v135, v84, v85
	ds_read_b64_tr_b16 v[68:69], v189 offset:47104
	ds_read_b64_tr_b16 v[70:71], v189 offset:47616
	s_waitcnt lgkmcnt(14)
	v_mfma_f32_32x32x16_bf16 v[48:63], v[170:173], v[150:153], v[48:63]
	v_add_f32_e32 v80, v88, v80
	v_add_f32_e32 v80, v89, v80
	v_add_f32_e32 v80, v90, v80
	v_add_f32_e32 v80, v91, v80
	v_cvt_pk_bf16_f32 v136, v86, v87
	v_cvt_pk_bf16_f32 v137, v88, v89
	ds_read_b64_tr_b16 v[84:85], v189 offset:44032
	ds_read_b64_tr_b16 v[86:87], v189 offset:44544
	s_waitcnt lgkmcnt(14)
	v_mfma_f32_32x32x16_bf16 v[114:129], v[72:75], v[146:149], v[114:129]
	v_add_f32_e32 v72, v92, v80
	v_add_f32_e32 v72, v93, v72
	v_add_f32_e32 v72, v94, v72
	v_add_f32_e32 v80, v95, v72
	v_cvt_pk_bf16_f32 v130, v90, v91
	v_cvt_pk_bf16_f32 v131, v92, v93
	ds_read_b64_tr_b16 v[72:73], v189 offset:48128
	ds_read_b64_tr_b16 v[74:75], v189 offset:48640
	v_mfma_f32_32x32x16_bf16 v[48:63], v[64:67], v[146:149], v[48:63]
	v_add_f32_e32 v64, v96, v80
	v_add_f32_e32 v64, v97, v64
	v_add_f32_e32 v64, 0, v64
	v_cvt_pk_bf16_f32 v132, v94, v95
	v_cvt_pk_bf16_f32 v133, v96, v97
	s_add_u32 s10, s10, 0xbd0000
	s_addc_u32 s11, s11, 0
	s_mov_b32 s19, m0
	s_mov_b32 m0, s18
	s_nop 0
	global_load_lds_dwordx4 v184, s[10:11]
	s_mov_b32 m0, s19
	s_add_u32 s10, s8, 0xb70000
	s_addc_u32 s11, s9, 0
	s_add_i32 s18, s17, 0x8000
	s_mov_b32 s19, m0
	s_mov_b32 m0, s18
	s_nop 0
	global_load_lds_dwordx4 v185, s[10:11]
	s_mov_b32 m0, s19
	v_add_f32_e32 v178, v183, v64
	s_waitcnt lgkmcnt(14)
	v_mfma_f32_32x32x16_bf16 v[0:15], v[142:145], v[174:177], v[0:15]
	v_exp_f32_e32 v114, v114
	v_exp_f32_e32 v115, v115
	v_exp_f32_e32 v116, v116
	v_exp_f32_e32 v117, v117
	s_waitcnt lgkmcnt(12)
	v_mfma_f32_32x32x16_bf16 v[16:31], v[142:145], v[98:101], v[16:31]
	v_exp_f32_e32 v118, v118
	v_exp_f32_e32 v119, v119
	v_exp_f32_e32 v120, v120
	v_exp_f32_e32 v121, v121
	ds_read_b128 v[64:67], v187 offset:8192
	ds_read_b128 v[88:91], v187 offset:8704
	s_waitcnt lgkmcnt(12)
	v_mfma_f32_32x32x16_bf16 v[0:15], v[138:141], v[76:79], v[0:15]
	v_exp_f32_e32 v122, v122
	v_exp_f32_e32 v123, v123
	v_exp_f32_e32 v124, v124
	v_exp_f32_e32 v125, v125
	ds_read_b128 v[92:95], v187 offset:10240
	ds_read_b128 v[162:165], v187 offset:10752
	s_waitcnt lgkmcnt(12)
	v_mfma_f32_32x32x16_bf16 v[16:31], v[138:141], v[102:105], v[16:31]
	v_exp_f32_e32 v126, v126
	v_exp_f32_e32 v127, v127
	v_exp_f32_e32 v128, v128
	v_exp_f32_e32 v129, v129
	ds_read_b128 v[166:169], v187 offset:12288
	ds_read_b128 v[170:173], v187 offset:12800
	s_waitcnt lgkmcnt(12)
	v_mfma_f32_32x32x16_bf16 v[0:15], v[134:137], v[106:109], v[0:15]
	v_exp_f32_e32 v48, v48
	v_exp_f32_e32 v49, v49
	v_exp_f32_e32 v50, v50
	v_exp_f32_e32 v51, v51
	ds_read_b128 v[174:177], v187 offset:14336
	ds_read_b128 v[80:83], v187 offset:14848
	s_waitcnt lgkmcnt(12)
	v_mfma_f32_32x32x16_bf16 v[16:31], v[134:137], v[68:71], v[16:31]
	v_exp_f32_e32 v52, v52
	v_exp_f32_e32 v53, v53
	v_exp_f32_e32 v54, v54
	v_exp_f32_e32 v55, v55
	s_waitcnt lgkmcnt(10)
	v_mfma_f32_32x32x16_bf16 v[0:15], v[130:133], v[84:87], v[0:15]
	v_exp_f32_e32 v56, v56
	v_exp_f32_e32 v57, v57
	v_exp_f32_e32 v58, v58
	v_exp_f32_e32 v59, v59
	s_waitcnt lgkmcnt(8)
	v_mfma_f32_32x32x16_bf16 v[16:31], v[130:133], v[72:75], v[16:31]
	v_exp_f32_e32 v60, v60
	v_exp_f32_e32 v61, v61
	v_exp_f32_e32 v62, v62
	v_exp_f32_e32 v63, v63
	s_waitcnt vmcnt(2) lgkmcnt(0)
	s_barrier
; #define WAIT_BAR(N) asm volatile("s_waitcnt vmcnt(" #N ") lgkmcnt(0)\n\ts_barrier" ::: "memory")
;   #define RESC() do { if constexpr (!NOMAX) if (resc) { asm volatile("s_waitcnt lgkmcnt(0)" ::: "memory"); \
;       _Pragma("unroll") for (int d_ = 0; d_ < 2 * DV2; ++d_) _Pragma("unroll") for (int r = 0; r < 16; ++r) o[d_][r] *= wsf[crow(r, hi)]; } } while (0)
;   #define ROT() do { sl_prev = sl_cur; sl_cur = sl_next; sl_next = (sl_next == (NSLOT - 1) * SLOTB) ? 0 : sl_next + SLOTB; } while (0)
;   #define ENDW(tt) do { if constexpr (DV2 == 2) { if ((tt) + 3 < NT) { WAIT_BAR(3); } else if ((tt) + 2 < NT) { WAIT_BAR(2); } else { WAIT_BAR(0); } } \
;     else { if ((tt) + 3 < NT) { WAIT_BAR(2); } else if ((tt) + 2 < NT) { WAIT_BAR(1); } else { WAIT_BAR(0); } } } while (0)
;     ...
;   int t = 1;
;   for (; t + 5 < NT; t += 2) {
;     STEP(pB0, pB1, pA0, pA1, t, true, true, true);     if constexpr (DV2 == 2) { WAIT_BAR(3); } else { WAIT_BAR(2); } RESC(); ROT();
;     STEP(pA0, pA1, pB0, pB1, t + 1, true, true, true); if constexpr (DV2 == 2) { WAIT_BAR(3); } else { WAIT_BAR(2); } RESC(); ROT();
;   }
;     ...
;   for (; t + 1 < NT; t += 2) {
;     STEP(pB0, pB1, pA0, pA1, t, (t + 3 < NT), (t + 1 < NT), (t + 1 < NT));         ENDW(t);     RESC(); ROT();
;     STEP(pA0, pA1, pB0, pB1, t + 1, (t + 4 < NT), (t + 2 < NT), (t + 2 < NT));     ENDW(t + 1); RESC(); ROT();
	ds_read_b64_tr_b16 v[84:85], v189 offset:24576
	ds_read_b64_tr_b16 v[86:87], v189 offset:25088
	v_add_f32_e32 v68, v114, v115
	v_add_f32_e32 v68, v116, v68
	v_add_f32_e32 v68, v117, v68
	v_add_f32_e32 v68, v118, v68
	v_add_f32_e32 v68, v119, v68
	v_cvt_pk_bf16_f32 v142, v114, v115
	v_cvt_pk_bf16_f32 v143, v116, v117
	s_waitcnt lgkmcnt(9)
	v_mfma_f32_32x32x16_bf16 v[96:111], v[64:67], v[158:161], v[32:47]
	ds_read_b64_tr_b16 v[112:113], v189 offset:28672
	ds_read_b64_tr_b16 v[114:115], v189 offset:29184
	v_add_f32_e32 v64, v120, v68
	v_add_f32_e32 v64, v121, v64
	v_add_f32_e32 v64, v122, v64
	v_add_f32_e32 v116, v123, v64
	v_cvt_pk_bf16_f32 v144, v118, v119
	v_cvt_pk_bf16_f32 v145, v120, v121
	s_waitcnt lgkmcnt(10)
	v_mfma_f32_32x32x16_bf16 v[64:79], v[88:91], v[158:161], v[32:47]
	ds_read_b64_tr_b16 v[88:89], v189 offset:25600
	ds_read_b64_tr_b16 v[90:91], v189 offset:26112
	s_waitcnt lgkmcnt(11)
	v_mfma_f32_32x32x16_bf16 v[96:111], v[92:95], v[154:157], v[96:111]
	v_add_f32_e32 v92, v124, v116
	v_add_f32_e32 v92, v125, v92
	v_add_f32_e32 v92, v126, v92
	v_add_f32_e32 v116, v127, v92
	v_cvt_pk_bf16_f32 v138, v122, v123
	v_cvt_pk_bf16_f32 v139, v124, v125
	ds_read_b64_tr_b16 v[92:93], v189 offset:29696
	ds_read_b64_tr_b16 v[94:95], v189 offset:30208
	v_add_f32_e32 v116, v128, v116
	v_add_f32_e32 v116, v129, v116
	v_add_f32_e32 v116, v48, v116
	v_add_f32_e32 v120, v49, v116
	v_cvt_pk_bf16_f32 v140, v126, v127
	v_cvt_pk_bf16_f32 v141, v128, v129
	s_waitcnt lgkmcnt(12)
	v_mfma_f32_32x32x16_bf16 v[64:79], v[162:165], v[154:157], v[64:79]
	ds_read_b64_tr_b16 v[116:117], v189 offset:26624
	ds_read_b64_tr_b16 v[118:119], v189 offset:27136
	v_add_f32_e32 v120, v50, v120
	v_add_f32_e32 v120, v51, v120
	v_add_f32_e32 v120, v52, v120
	v_add_f32_e32 v120, v53, v120
	v_cvt_pk_bf16_f32 v134, v48, v49
	v_cvt_pk_bf16_f32 v135, v50, v51
	s_waitcnt lgkmcnt(13)
	v_mfma_f32_32x32x16_bf16 v[96:111], v[166:169], v[150:153], v[96:111]
	ds_read_b64_tr_b16 v[48:49], v189 offset:30720
	ds_read_b64_tr_b16 v[50:51], v189 offset:31232
	v_add_f32_e32 v120, v54, v120
	v_add_f32_e32 v120, v55, v120
	v_add_f32_e32 v120, v56, v120
	v_add_f32_e32 v120, v57, v120
	v_cvt_pk_bf16_f32 v136, v52, v53
	v_cvt_pk_bf16_f32 v137, v54, v55
	s_waitcnt lgkmcnt(14)
	v_mfma_f32_32x32x16_bf16 v[64:79], v[170:173], v[150:153], v[64:79]
	ds_read_b64_tr_b16 v[52:53], v189 offset:27648
	ds_read_b64_tr_b16 v[54:55], v189 offset:28160
	v_add_f32_e32 v120, v58, v120
	v_add_f32_e32 v120, v59, v120
	v_add_f32_e32 v120, v60, v120
	v_add_f32_e32 v120, v61, v120
	v_cvt_pk_bf16_f32 v130, v56, v57
	v_cvt_pk_bf16_f32 v131, v58, v59
	s_waitcnt lgkmcnt(14)
	v_mfma_f32_32x32x16_bf16 v[96:111], v[174:177], v[146:149], v[96:111]
	ds_read_b64_tr_b16 v[56:57], v189 offset:31744
	ds_read_b64_tr_b16 v[58:59], v189 offset:32256
	v_mfma_f32_32x32x16_bf16 v[64:79], v[80:83], v[146:149], v[64:79]
	v_add_f32_e32 v80, v62, v120
	v_add_f32_e32 v80, v63, v80
	v_add_f32_e32 v80, 0, v80
	v_cvt_pk_bf16_f32 v132, v60, v61
	v_cvt_pk_bf16_f32 v133, v62, v63
	s_add_u32 s10, s8, 0xba0000
	s_addc_u32 s11, s9, 0
	s_add_i32 s17, s17, 0xa000
	s_mov_b32 s18, m0
	s_mov_b32 m0, s17
	s_nop 0
	global_load_lds_dwordx4 v185, s[10:11]
	s_mov_b32 m0, s18
	v_add_f32_e32 v128, v178, v80
	s_waitcnt lgkmcnt(14)
	v_mfma_f32_32x32x16_bf16 v[0:15], v[142:145], v[84:87], v[0:15]
	v_exp_f32_e32 v96, v96
	v_exp_f32_e32 v97, v97
	v_exp_f32_e32 v98, v98
	v_exp_f32_e32 v99, v99
	s_waitcnt lgkmcnt(12)
	v_mfma_f32_32x32x16_bf16 v[16:31], v[142:145], v[112:115], v[16:31]
	v_exp_f32_e32 v100, v100
	v_exp_f32_e32 v101, v101
	v_exp_f32_e32 v102, v102
	v_exp_f32_e32 v103, v103
	ds_read_b128 v[60:63], v187 offset:16384
	ds_read_b128 v[120:123], v187 offset:16896
	s_waitcnt lgkmcnt(12)
	v_mfma_f32_32x32x16_bf16 v[0:15], v[138:141], v[88:91], v[0:15]
	v_exp_f32_e32 v104, v104
	v_exp_f32_e32 v105, v105
	v_exp_f32_e32 v106, v106
	v_exp_f32_e32 v107, v107
	ds_read_b128 v[124:127], v187 offset:18432
	ds_read_b128 v[162:165], v187 offset:18944
	s_waitcnt lgkmcnt(12)
	v_mfma_f32_32x32x16_bf16 v[16:31], v[138:141], v[92:95], v[16:31]
	v_exp_f32_e32 v108, v108
	v_exp_f32_e32 v109, v109
	v_exp_f32_e32 v110, v110
	v_exp_f32_e32 v111, v111
	ds_read_b128 v[166:169], v187 offset:20480
	ds_read_b128 v[170:173], v187 offset:20992
	s_waitcnt lgkmcnt(12)
	v_mfma_f32_32x32x16_bf16 v[0:15], v[134:137], v[116:119], v[0:15]
	v_exp_f32_e32 v64, v64
	v_exp_f32_e32 v65, v65
	v_exp_f32_e32 v66, v66
	v_exp_f32_e32 v67, v67
	ds_read_b128 v[116:119], v187 offset:22528
	ds_read_b128 v[112:115], v187 offset:23040
	s_waitcnt lgkmcnt(12)
	v_mfma_f32_32x32x16_bf16 v[16:31], v[134:137], v[48:51], v[16:31]
	v_exp_f32_e32 v68, v68
	v_exp_f32_e32 v69, v69
	v_exp_f32_e32 v70, v70
	v_exp_f32_e32 v71, v71
	s_waitcnt lgkmcnt(10)
	v_mfma_f32_32x32x16_bf16 v[0:15], v[130:133], v[52:55], v[0:15]
	v_exp_f32_e32 v72, v72
	v_exp_f32_e32 v73, v73
	v_exp_f32_e32 v74, v74
	v_exp_f32_e32 v75, v75
	s_waitcnt lgkmcnt(8)
	v_mfma_f32_32x32x16_bf16 v[16:31], v[130:133], v[56:59], v[16:31]
	v_exp_f32_e32 v76, v76
	v_exp_f32_e32 v77, v77
	v_exp_f32_e32 v78, v78
	v_exp_f32_e32 v79, v79
	s_waitcnt vmcnt(1) lgkmcnt(0)
	s_barrier
; #define WAIT_BAR(N) asm volatile("s_waitcnt vmcnt(" #N ") lgkmcnt(0)\n\ts_barrier" ::: "memory")
;   #define RESC() do { if constexpr (!NOMAX) if (resc) { asm volatile("s_waitcnt lgkmcnt(0)" ::: "memory"); \
;       _Pragma("unroll") for (int d_ = 0; d_ < 2 * DV2; ++d_) _Pragma("unroll") for (int r = 0; r < 16; ++r) o[d_][r] *= wsf[crow(r, hi)]; } } while (0)
;   #define ROT() do { sl_prev = sl_cur; sl_cur = sl_next; sl_next = (sl_next == (NSLOT - 1) * SLOTB) ? 0 : sl_next + SLOTB; } while (0)
;   #define ENDW(tt) do { if constexpr (DV2 == 2) { if ((tt) + 3 < NT) { WAIT_BAR(3); } else if ((tt) + 2 < NT) { WAIT_BAR(2); } else { WAIT_BAR(0); } } \
;     else { if ((tt) + 3 < NT) { WAIT_BAR(2); } else if ((tt) + 2 < NT) { WAIT_BAR(1); } else { WAIT_BAR(0); } } } while (0)
;     ...
;   int t = 1;
;   for (; t + 5 < NT; t += 2) {
;     STEP(pB0, pB1, pA0, pA1, t, true, true, true);     if constexpr (DV2 == 2) { WAIT_BAR(3); } else { WAIT_BAR(2); } RESC(); ROT();
;     STEP(pA0, pA1, pB0, pB1, t + 1, true, true, true); if constexpr (DV2 == 2) { WAIT_BAR(3); } else { WAIT_BAR(2); } RESC(); ROT();
;   }
;     ...
;   for (; t + 1 < NT; t += 2) {
;     STEP(pB0, pB1, pA0, pA1, t, (t + 3 < NT), (t + 1 < NT), (t + 1 < NT));         ENDW(t);     RESC(); ROT();
;     STEP(pA0, pA1, pB0, pB1, t + 1, (t + 4 < NT), (t + 2 < NT), (t + 2 < NT));     ENDW(t + 1); RESC(); ROT();
	ds_read_b64_tr_b16 v[174:175], v189 offset:32768
	ds_read_b64_tr_b16 v[176:177], v189 offset:33280
	v_add_f32_e32 v48, v96, v97
	v_add_f32_e32 v48, v98, v48
	v_add_f32_e32 v48, v99, v48
	v_add_f32_e32 v48, v100, v48
	v_add_f32_e32 v48, v101, v48
	v_cvt_pk_bf16_f32 v142, v96, v97
	v_cvt_pk_bf16_f32 v143, v98, v99
	s_waitcnt lgkmcnt(9)
	v_mfma_f32_32x32x16_bf16 v[80:95], v[60:63], v[158:161], v[32:47]
	ds_read_b64_tr_b16 v[96:97], v189 offset:36864
	ds_read_b64_tr_b16 v[98:99], v189 offset:37376
	v_add_f32_e32 v48, v102, v48
	v_add_f32_e32 v48, v103, v48
	v_add_f32_e32 v48, v104, v48
	v_add_f32_e32 v129, v105, v48
	s_waitcnt lgkmcnt(10)
	v_mfma_f32_32x32x16_bf16 v[48:63], v[120:123], v[158:161], v[32:47]
	v_cvt_pk_bf16_f32 v144, v100, v101
	v_cvt_pk_bf16_f32 v145, v102, v103
	ds_read_b64_tr_b16 v[100:101], v189 offset:33792
	ds_read_b64_tr_b16 v[102:103], v189 offset:34304
	v_add_f32_e32 v120, v106, v129
	v_add_f32_e32 v120, v107, v120
	v_add_f32_e32 v120, v108, v120
	v_add_f32_e32 v120, v109, v120
	v_cvt_pk_bf16_f32 v138, v104, v105
	v_cvt_pk_bf16_f32 v139, v106, v107
	s_waitcnt lgkmcnt(11)
	v_mfma_f32_32x32x16_bf16 v[80:95], v[124:127], v[154:157], v[80:95]
	ds_read_b64_tr_b16 v[104:105], v189 offset:37888
	ds_read_b64_tr_b16 v[106:107], v189 offset:38400
	s_waitcnt lgkmcnt(12)
	v_mfma_f32_32x32x16_bf16 v[48:63], v[162:165], v[154:157], v[48:63]
	v_add_f32_e32 v120, v110, v120
	v_add_f32_e32 v120, v111, v120
	v_add_f32_e32 v120, v64, v120
	v_add_f32_e32 v124, v65, v120
	v_cvt_pk_bf16_f32 v140, v108, v109
	v_cvt_pk_bf16_f32 v141, v110, v111
	ds_read_b64_tr_b16 v[120:121], v189 offset:34816
	ds_read_b64_tr_b16 v[122:123], v189 offset:35328
	v_add_f32_e32 v108, v66, v124
	v_add_f32_e32 v108, v67, v108
	v_add_f32_e32 v108, v68, v108
	v_add_f32_e32 v108, v69, v108
	v_cvt_pk_bf16_f32 v134, v64, v65
	v_cvt_pk_bf16_f32 v135, v66, v67
	s_waitcnt lgkmcnt(13)
	v_mfma_f32_32x32x16_bf16 v[80:95], v[166:169], v[150:153], v[80:95]
	ds_read_b64_tr_b16 v[64:65], v189 offset:38912
	ds_read_b64_tr_b16 v[66:67], v189 offset:39424
	s_waitcnt lgkmcnt(14)
	v_mfma_f32_32x32x16_bf16 v[48:63], v[170:173], v[150:153], v[48:63]
	v_add_f32_e32 v108, v70, v108
	v_add_f32_e32 v108, v71, v108
	v_add_f32_e32 v108, v72, v108
	v_add_f32_e32 v108, v73, v108
	v_cvt_pk_bf16_f32 v136, v68, v69
	v_cvt_pk_bf16_f32 v137, v70, v71
	ds_read_b64_tr_b16 v[68:69], v189 offset:35840
	ds_read_b64_tr_b16 v[70:71], v189 offset:36352
	v_add_f32_e32 v108, v74, v108
	v_add_f32_e32 v108, v75, v108
	v_add_f32_e32 v108, v76, v108
	v_add_f32_e32 v108, v77, v108
	v_cvt_pk_bf16_f32 v130, v72, v73
	v_cvt_pk_bf16_f32 v131, v74, v75
	s_waitcnt lgkmcnt(14)
	v_mfma_f32_32x32x16_bf16 v[80:95], v[116:119], v[146:149], v[80:95]
	ds_read_b64_tr_b16 v[72:73], v189 offset:39936
	ds_read_b64_tr_b16 v[74:75], v189 offset:40448
	v_mfma_f32_32x32x16_bf16 v[48:63], v[112:115], v[146:149], v[48:63]
	v_add_f32_e32 v108, v78, v108
	v_add_f32_e32 v108, v79, v108
	v_add_f32_e32 v108, 0, v108
	v_cvt_pk_bf16_f32 v132, v76, v77
	v_cvt_pk_bf16_f32 v133, v78, v79
	s_add_u32 s8, s8, 0xbd0000
	s_addc_u32 s9, s9, 0
	s_mov_b32 s10, m0
	s_mov_b32 m0, s15
	s_nop 0
	global_load_lds_dwordx4 v185, s[8:9]
	s_mov_b32 m0, s10
	v_add_f32_e32 v108, v128, v108
	s_waitcnt lgkmcnt(14)
	v_mfma_f32_32x32x16_bf16 v[0:15], v[142:145], v[174:177], v[0:15]
	v_exp_f32_e32 v80, v80
	v_exp_f32_e32 v81, v81
	v_exp_f32_e32 v82, v82
	v_exp_f32_e32 v83, v83
	s_waitcnt lgkmcnt(12)
	v_mfma_f32_32x32x16_bf16 v[16:31], v[142:145], v[96:99], v[16:31]
	v_exp_f32_e32 v84, v84
	v_exp_f32_e32 v85, v85
	v_exp_f32_e32 v86, v86
	v_exp_f32_e32 v87, v87
	ds_read_b128 v[110:113], v187
	ds_read_b128 v[114:117], v187 offset:512
	s_waitcnt lgkmcnt(12)
	v_mfma_f32_32x32x16_bf16 v[0:15], v[138:141], v[100:103], v[0:15]
	v_exp_f32_e32 v88, v88
	v_exp_f32_e32 v89, v89
	v_exp_f32_e32 v90, v90
	v_exp_f32_e32 v91, v91
	ds_read_b128 v[124:127], v187 offset:2048
	ds_read_b128 v[162:165], v187 offset:2560
	s_waitcnt lgkmcnt(12)
	v_mfma_f32_32x32x16_bf16 v[16:31], v[138:141], v[104:107], v[16:31]
	v_exp_f32_e32 v92, v92
	v_exp_f32_e32 v93, v93
	v_exp_f32_e32 v94, v94
	v_exp_f32_e32 v95, v95
	ds_read_b128 v[166:169], v187 offset:4096
	ds_read_b128 v[170:173], v187 offset:4608
	s_waitcnt lgkmcnt(12)
	v_mfma_f32_32x32x16_bf16 v[0:15], v[134:137], v[120:123], v[0:15]
	v_exp_f32_e32 v48, v48
	v_exp_f32_e32 v49, v49
	v_exp_f32_e32 v50, v50
	v_exp_f32_e32 v51, v51
	ds_read_b128 v[118:121], v187 offset:6144
	ds_read_b128 v[104:107], v187 offset:6656
	s_waitcnt lgkmcnt(12)
	v_mfma_f32_32x32x16_bf16 v[16:31], v[134:137], v[64:67], v[16:31]
	v_exp_f32_e32 v52, v52
	v_exp_f32_e32 v53, v53
	v_exp_f32_e32 v54, v54
	v_exp_f32_e32 v55, v55
	s_waitcnt lgkmcnt(10)
	v_mfma_f32_32x32x16_bf16 v[0:15], v[130:133], v[68:71], v[0:15]
	v_exp_f32_e32 v56, v56
	v_exp_f32_e32 v57, v57
	v_exp_f32_e32 v58, v58
	v_exp_f32_e32 v59, v59
	s_waitcnt lgkmcnt(8)
	v_mfma_f32_32x32x16_bf16 v[16:31], v[130:133], v[72:75], v[16:31]
	v_exp_f32_e32 v60, v60
	v_exp_f32_e32 v61, v61
	v_exp_f32_e32 v62, v62
	v_exp_f32_e32 v63, v63
	s_waitcnt vmcnt(0) lgkmcnt(0)
	s_barrier
	ds_read_b64_tr_b16 v[96:97], v189 offset:40960
	ds_read_b64_tr_b16 v[98:99], v189 offset:41472
	v_add_f32_e32 v64, v80, v81
	v_add_f32_e32 v64, v82, v64
	v_add_f32_e32 v64, v83, v64
	v_add_f32_e32 v64, v84, v64
	v_add_f32_e32 v100, v85, v64
	v_cvt_pk_bf16_f32 v142, v80, v81
	v_cvt_pk_bf16_f32 v143, v82, v83
	s_waitcnt lgkmcnt(9)
	v_mfma_f32_32x32x16_bf16 v[64:79], v[110:113], v[158:161], v[32:47]
	ds_read_b64_tr_b16 v[80:81], v189 offset:45056
	ds_read_b64_tr_b16 v[82:83], v189 offset:45568
	s_waitcnt lgkmcnt(10)
	v_mfma_f32_32x32x16_bf16 v[32:47], v[114:117], v[158:161], v[32:47]
	v_add_f32_e32 v100, v86, v100
	v_add_f32_e32 v100, v87, v100
	v_add_f32_e32 v100, v88, v100
	v_add_f32_e32 v109, v89, v100
	v_cvt_pk_bf16_f32 v144, v84, v85
	v_cvt_pk_bf16_f32 v145, v86, v87
	ds_read_b64_tr_b16 v[100:101], v189 offset:41984
	ds_read_b64_tr_b16 v[102:103], v189 offset:42496
	v_add_f32_e32 v84, v90, v109
	v_add_f32_e32 v84, v91, v84
	v_add_f32_e32 v84, v92, v84
	v_add_f32_e32 v109, v93, v84
	v_cvt_pk_bf16_f32 v138, v88, v89
	v_cvt_pk_bf16_f32 v139, v90, v91
	s_waitcnt lgkmcnt(11)
	v_mfma_f32_32x32x16_bf16 v[64:79], v[124:127], v[154:157], v[64:79]
	ds_read_b64_tr_b16 v[84:85], v189 offset:46080
	ds_read_b64_tr_b16 v[86:87], v189 offset:46592
	s_waitcnt lgkmcnt(12)
	v_mfma_f32_32x32x16_bf16 v[32:47], v[162:165], v[154:157], v[32:47]
	v_add_f32_e32 v88, v94, v109
	v_add_f32_e32 v88, v95, v88
	v_add_f32_e32 v88, v48, v88
	v_add_f32_e32 v109, v49, v88
	v_cvt_pk_bf16_f32 v140, v92, v93
	v_cvt_pk_bf16_f32 v141, v94, v95
	ds_read_b64_tr_b16 v[88:89], v189 offset:43008
	ds_read_b64_tr_b16 v[90:91], v189 offset:43520
	v_add_f32_e32 v92, v50, v109
	v_add_f32_e32 v92, v51, v92
	v_add_f32_e32 v92, v52, v92
	v_add_f32_e32 v92, v53, v92
	v_cvt_pk_bf16_f32 v134, v48, v49
	v_cvt_pk_bf16_f32 v135, v50, v51
	s_waitcnt lgkmcnt(13)
	v_mfma_f32_32x32x16_bf16 v[64:79], v[166:169], v[150:153], v[64:79]
	ds_read_b64_tr_b16 v[48:49], v189 offset:47104
	ds_read_b64_tr_b16 v[50:51], v189 offset:47616
	s_waitcnt lgkmcnt(14)
	v_mfma_f32_32x32x16_bf16 v[32:47], v[170:173], v[150:153], v[32:47]
	v_add_f32_e32 v92, v54, v92
	v_add_f32_e32 v92, v55, v92
	v_add_f32_e32 v92, v56, v92
	v_add_f32_e32 v109, v57, v92
	v_cvt_pk_bf16_f32 v136, v52, v53
	v_cvt_pk_bf16_f32 v137, v54, v55
	ds_read_b64_tr_b16 v[92:93], v189 offset:44032
	ds_read_b64_tr_b16 v[94:95], v189 offset:44544
	v_add_f32_e32 v52, v58, v109
	v_add_f32_e32 v52, v59, v52
	v_add_f32_e32 v52, v60, v52
	v_add_f32_e32 v109, v61, v52
	v_cvt_pk_bf16_f32 v130, v56, v57
	v_cvt_pk_bf16_f32 v131, v58, v59
	s_waitcnt lgkmcnt(14)
	v_mfma_f32_32x32x16_bf16 v[64:79], v[118:121], v[146:149], v[64:79]
	ds_read_b64_tr_b16 v[52:53], v189 offset:48128
	ds_read_b64_tr_b16 v[54:55], v189 offset:48640
	v_mfma_f32_32x32x16_bf16 v[32:47], v[104:107], v[146:149], v[32:47]
	v_add_f32_e32 v56, v62, v109
	v_add_f32_e32 v56, v63, v56
	v_add_f32_e32 v56, 0, v56
	v_cvt_pk_bf16_f32 v132, v60, v61
	v_cvt_pk_bf16_f32 v133, v62, v63
	s_nop 3
	v_exp_f32_e32 v64, v64
	v_exp_f32_e32 v65, v65
	v_exp_f32_e32 v66, v66
	v_exp_f32_e32 v67, v67
	s_nop 0
	v_exp_f32_e32 v68, v68
	v_exp_f32_e32 v69, v69
	v_exp_f32_e32 v70, v70
	v_exp_f32_e32 v71, v71
	s_nop 0
	v_exp_f32_e32 v72, v72
	v_exp_f32_e32 v73, v73
	v_exp_f32_e32 v74, v74
	v_exp_f32_e32 v75, v75
	s_nop 0
	v_exp_f32_e32 v76, v76
	v_exp_f32_e32 v77, v77
	v_exp_f32_e32 v78, v78
	v_exp_f32_e32 v79, v79
	v_exp_f32_e32 v32, v32
	v_exp_f32_e32 v33, v33
	v_exp_f32_e32 v34, v34
	v_exp_f32_e32 v35, v35
	s_nop 0
	v_exp_f32_e32 v36, v36
	v_exp_f32_e32 v37, v37
	v_exp_f32_e32 v38, v38
	v_exp_f32_e32 v39, v39
	s_nop 0
	v_exp_f32_e32 v40, v40
	v_exp_f32_e32 v41, v41
	v_exp_f32_e32 v42, v42
	v_exp_f32_e32 v43, v43
	s_nop 0
	v_exp_f32_e32 v44, v44
	v_exp_f32_e32 v45, v45
	v_exp_f32_e32 v46, v46
	v_exp_f32_e32 v47, v47
	s_waitcnt lgkmcnt(14)
; #define SBAR() __builtin_amdgcn_sched_barrier(0)
; #define WAIT_BAR(N) asm volatile("s_waitcnt vmcnt(" #N ") lgkmcnt(0)\n\ts_barrier" ::: "memory")
;   #define RESC() do { if constexpr (!NOMAX) if (resc) { asm volatile("s_waitcnt lgkmcnt(0)" ::: "memory"); \
;       _Pragma("unroll") for (int d_ = 0; d_ < 2 * DV2; ++d_) _Pragma("unroll") for (int r = 0; r < 16; ++r) o[d_][r] *= wsf[crow(r, hi)]; } } while (0)
;   #define ROT() do { sl_prev = sl_cur; sl_cur = sl_next; sl_next = (sl_next == (NSLOT - 1) * SLOTB) ? 0 : sl_next + SLOTB; } while (0)
;   #define PKW(P, B) cvtpk_s(P[B], P[B + 1])
;     ...
;   int t = 1;
;   for (; t + 5 < NT; t += 2) {
;     STEP(pB0, pB1, pA0, pA1, t, true, true, true);     if constexpr (DV2 == 2) { WAIT_BAR(3); } else { WAIT_BAR(2); } RESC(); ROT();
;     STEP(pA0, pA1, pB0, pB1, t + 1, true, true, true); if constexpr (DV2 == 2) { WAIT_BAR(3); } else { WAIT_BAR(2); } RESC(); ROT();
;   }
;     ...
;   for (; t + 1 < NT; t += 2) {
;     STEP(pB0, pB1, pA0, pA1, t, (t + 3 < NT), (t + 1 < NT), (t + 1 < NT));         ENDW(t);     RESC(); ROT();
;     STEP(pA0, pA1, pB0, pB1, t + 1, (t + 4 < NT), (t + 2 < NT), (t + 2 < NT));     ENDW(t + 1); RESC(); ROT();
;   }
;   STEP(pB0, pB1, pA0, pA1, NT - 1, false, false, false); RESC();
;   { float sacc = pB0[0] + pB0[1]; _Pragma("unroll") for (int r = 2; r < 16; ++r) sacc += pB0[r]; _Pragma("unroll") for (int r = 0; r < 16; ++r) sacc += pB1[r]; l_reg += sacc;
;     pw0 = (u32x4){PKW(pB0, 0), PKW(pB0, 2), PKW(pB0, 4), PKW(pB0, 6)}; pw1 = (u32x4){PKW(pB0, 8), PKW(pB0, 10), PKW(pB0, 12), PKW(pB0, 14)}; pw2 = (u32x4){PKW(pB1, 0), PKW(pB1, 2), PKW(pB1, 4), PKW(pB1, 6)}; pw3 = (u32x4){PKW(pB1, 8), PKW(pB1, 10), PKW(pB1, 12), PKW(pB1, 14)};
;     SBAR(); pv(o, vb0 + DV2 * sl_cur, PAF(0), PAF(1), PAF(2), PAF(3)); if constexpr (DV2 == 2) pv(o + 2, vb0 + DV2 * sl_cur + 8192, PAF(0), PAF(1), PAF(2), PAF(3)); }
;     ...
;   { auto rr = __builtin_amdgcn_permlane32_swap(__float_as_uint(l_reg), __float_as_uint(l_reg), false, false); l_reg = __uint_as_float(rr[0]) + __uint_as_float(rr[1]); }
;   int lane_e; asm volatile("v_mbcnt_lo_u32_b32 %0, -1, 0\n\tv_mbcnt_hi_u32_b32 %0, -1, %0" : "=v"(lane_e));
;   const int r32e = lane_e & 31, hie = lane_e >> 5;
;   if (hie == 0) wsf[32 + r32e] = l_reg; asm volatile("s_waitcnt lgkmcnt(0)" ::: "memory");
	v_mfma_f32_32x32x16_bf16 v[0:15], v[142:145], v[96:99], v[0:15]
	v_add_f32_e32 v57, v64, v65
	v_add_f32_e32 v57, v66, v57
	v_add_f32_e32 v57, v67, v57
	v_add_f32_e32 v57, v68, v57
	v_add_f32_e32 v57, v69, v57
	v_add_f32_e32 v57, v70, v57
	v_add_f32_e32 v57, v71, v57
	s_waitcnt lgkmcnt(12)
	v_mfma_f32_32x32x16_bf16 v[16:31], v[142:145], v[80:83], v[16:31]
	v_add_f32_e32 v57, v72, v57
	v_add_f32_e32 v57, v73, v57
	v_add_f32_e32 v57, v74, v57
	v_add_f32_e32 v57, v75, v57
	v_add_f32_e32 v57, v76, v57
	v_add_f32_e32 v57, v77, v57
	v_add_f32_e32 v57, v78, v57
	s_waitcnt lgkmcnt(10)
	v_mfma_f32_32x32x16_bf16 v[0:15], v[138:141], v[100:103], v[0:15]
	v_add_f32_e32 v57, v79, v57
	v_add_f32_e32 v57, v32, v57
	v_add_f32_e32 v57, v33, v57
	v_add_f32_e32 v57, v34, v57
	v_add_f32_e32 v57, v35, v57
	v_add_f32_e32 v57, v36, v57
	v_add_f32_e32 v57, v37, v57
	s_waitcnt lgkmcnt(8)
	v_mfma_f32_32x32x16_bf16 v[16:31], v[138:141], v[84:87], v[16:31]
	v_add_f32_e32 v57, v38, v57
	v_add_f32_e32 v57, v39, v57
	v_add_f32_e32 v57, v40, v57
	v_add_f32_e32 v57, v41, v57
	v_add_f32_e32 v57, v42, v57
	v_add_f32_e32 v57, v43, v57
	v_add_f32_e32 v57, v44, v57
	s_waitcnt lgkmcnt(6)
	v_mfma_f32_32x32x16_bf16 v[0:15], v[134:137], v[88:91], v[0:15]
	v_add_f32_e32 v57, v45, v57
	v_add_f32_e32 v57, v46, v57
	v_add_f32_e32 v57, v47, v57
	v_add_f32_e32 v56, v108, v56
	v_add_f32_e32 v56, v56, v57
	v_cvt_pk_bf16_f32 v32, v32, v33
	v_cvt_pk_bf16_f32 v33, v34, v35
	s_waitcnt lgkmcnt(4)
	v_mfma_f32_32x32x16_bf16 v[16:31], v[134:137], v[48:51], v[16:31]
	v_cvt_pk_bf16_f32 v58, v64, v65
	v_cvt_pk_bf16_f32 v59, v66, v67
	v_cvt_pk_bf16_f32 v60, v68, v69
	v_cvt_pk_bf16_f32 v61, v70, v71
	v_cvt_pk_bf16_f32 v62, v72, v73
	v_cvt_pk_bf16_f32 v63, v74, v75
	v_cvt_pk_bf16_f32 v64, v76, v77
	s_waitcnt lgkmcnt(2)
	v_mfma_f32_32x32x16_bf16 v[0:15], v[130:133], v[92:95], v[0:15]
	v_cvt_pk_bf16_f32 v65, v78, v79
	v_cvt_pk_bf16_f32 v34, v36, v37
	v_cvt_pk_bf16_f32 v35, v38, v39
	v_cvt_pk_bf16_f32 v36, v40, v41
	v_cvt_pk_bf16_f32 v37, v42, v43
	v_cvt_pk_bf16_f32 v38, v44, v45
	v_cvt_pk_bf16_f32 v39, v46, v47
	s_waitcnt lgkmcnt(0)
	v_mfma_f32_32x32x16_bf16 v[16:31], v[130:133], v[52:55], v[16:31]
	ds_read_b64_tr_b16 v[40:41],v188 offset:0
	ds_read_b64_tr_b16 v[42:43],v188 offset:512
	ds_read_b64_tr_b16 v[44:45],v188 offset:1024
	ds_read_b64_tr_b16 v[46:47],v188 offset:1536
	ds_read_b64_tr_b16 v[48:49],v188 offset:2048
	ds_read_b64_tr_b16 v[50:51],v188 offset:2560
	ds_read_b64_tr_b16 v[52:53],v188 offset:3072
	ds_read_b64_tr_b16 v[54:55],v188 offset:3584
	s_waitcnt lgkmcnt(0)
	s_nop 0
	v_mfma_f32_32x32x16_bf16 v[0:15], v[58:61], v[40:43], v[0:15]
	ds_read_b64_tr_b16 v[40:41],v188 offset:4096
	ds_read_b64_tr_b16 v[42:43],v188 offset:4608
	v_mfma_f32_32x32x16_bf16 v[0:15], v[62:65], v[44:47], v[0:15]
	ds_read_b64_tr_b16 v[44:45],v188 offset:5120
	ds_read_b64_tr_b16 v[46:47],v188 offset:5632
	v_mfma_f32_32x32x16_bf16 v[0:15], v[32:35], v[48:51], v[0:15]
	ds_read_b64_tr_b16 v[48:49],v188 offset:6144
	ds_read_b64_tr_b16 v[50:51],v188 offset:6656
	v_mfma_f32_32x32x16_bf16 v[0:15], v[36:39], v[52:55], v[0:15]
	ds_read_b64_tr_b16 v[52:53],v188 offset:7168
	ds_read_b64_tr_b16 v[54:55],v188 offset:7680
	s_waitcnt lgkmcnt(0)
	v_mfma_f32_32x32x16_bf16 v[16:31], v[58:61], v[40:43], v[16:31]
	v_mfma_f32_32x32x16_bf16 v[16:31], v[62:65], v[44:47], v[16:31]
	v_mfma_f32_32x32x16_bf16 v[16:31], v[32:35], v[48:51], v[16:31]
	v_mov_b32_e32 v33, v56
	s_nop 1
	v_permlane32_swap_b32_e32 v56, v33
	v_mbcnt_lo_u32_b32 v32, -1, 0
	v_mbcnt_hi_u32_b32 v32, -1, v32
	s_nop 0
	v_cmp_gt_u32_e32 vcc, 32, v32
	v_mfma_f32_32x32x16_bf16 v[16:31], v[36:39], v[52:55], v[16:31]
	s_and_saveexec_b64 s[8:9], vcc
	s_cbranch_execz .LBB0_968
	v_add_f32_e32 v33, v56, v33
	v_lshl_add_u32 v34, v32, 2, s16
	ds_write_b32 v34, v33 offset:49280
	s_branch .LBB0_968
